# swiglu epilogue: adjacent (a*-log2e) multiplies and (1+e) adds merged into packed f32 ops (same arithmetic), on top of mask rewrite + pool remap
# baseline (speedup 1.0000x reference)
_Z14fwd_megakernel4Args:
	s_load_dwordx2 s[46:47], s[0:1], 0xa8
	s_load_dword s3, s[0:1], 0xb0
	s_add_u32 s10, s0, 0xa8
	v_and_b32_e32 v224, 0x3ff, v0
	v_mov_b32_e32 v250, 0xbfb8aa3b
	s_addc_u32 s11, s1, 0
	v_cmp_gt_u32_e32 vcc, 2, v224
	s_and_saveexec_b64 s[4:5], vcc
	v_lshl_add_u32 v1, v224, 2, 0
	v_add_u32_e32 v1, 0x20040, v1
	v_mov_b32_e32 v2, 0
	ds_write_b32 v1, v2
	s_or_b64 exec, exec, s[4:5]
	s_mov_b32 s4, 20
	s_waitcnt lgkmcnt(0)
	s_barrier
	s_ashr_i32 s5, s4, 31
	s_lshl_b64 s[4:5], s[4:5], 3
	s_add_u32 s4, s0, s4
	s_addc_u32 s5, s1, s5
	s_load_dwordx2 s[38:39], s[4:5], 0x0
	s_getreg_b32 s6, hwreg(HW_REG_XCC_ID, 0, 4)
	s_mov_b32 s8, 20
	s_mov_b32 s4, 3
	s_mov_b32 s5, 15
	s_waitcnt lgkmcnt(0)
	s_add_u32 s40, s38, 0x70000
	s_addc_u32 s41, s39, 0
	s_and_b32 s33, s6, 15
	s_mov_b32 s9, 0
	v_cmp_eq_u32_e64 s[88:89], 0, v224
	s_and_saveexec_b64 s[6:7], s[88:89]
	s_cbranch_execz .LBB0_5
	s_mov_b64 s[12:13], exec
	v_mbcnt_lo_u32_b32 v1, s12, 0
	v_mbcnt_hi_u32_b32 v1, s13, v1
	v_cmp_eq_u32_e32 vcc, 0, v1
	s_and_b64 s[14:15], exec, vcc
	s_mov_b64 exec, s[14:15]
	s_cbranch_execz .LBB0_5
	s_lshl_b32 s14, s33, 8
	s_bcnt1_i32_b64 s12, s[12:13]
	v_mov_b32_e32 v1, s14
	v_mov_b32_e32 v2, s12
	global_atomic_add v1, v2, s[40:41] offset:1024

.LBB0_377:
	v_mul_f32_e32 v149, 0xbfb8aa3b, v122
	v_exp_f32_e32 v149, v149
	v_pk_mul_f32 v[128:129], v[128:129], v[124:125]
	v_pk_mul_f32 v[120:121], v[120:121], v[116:117]
	v_pk_mul_f32 v[112:113], v[112:113], v[108:109]
	v_add_f32_e32 v149, 1.0, v149
	v_rcp_f32_e32 v152, v149
	v_mul_f32_e32 v149, 0xbfb8aa3b, v123
	v_exp_f32_e32 v149, v149
	v_pk_mul_f32 v[122:123], v[126:127], v[122:123]
	v_pk_mul_f32 v[104:105], v[104:105], v[100:101]
	v_pk_mul_f32 v[96:97], v[96:97], v[92:93]
	v_add_f32_e32 v149, 1.0, v149
	v_rcp_f32_e32 v153, v149
	v_pk_mul_f32 v[88:89], v[88:89], v[84:85]
	v_pk_mul_f32 v[80:81], v[80:81], v[76:77]
	v_pk_mul_f32 v[72:73], v[72:73], v[68:69]
	v_pk_mul_f32 v[122:123], v[122:123], v[152:153]
	v_pk_mul_f32 v[64:65], v[64:65], v[60:61]
	v_cvt_pk_bf16_f32 v122, v122, v123
	v_mul_f32_e32 v123, 0xbfb8aa3b, v124
	v_exp_f32_e32 v123, v123
	v_pk_mul_f32 v[56:57], v[56:57], v[52:53]
	v_pk_mul_f32 v[48:49], v[48:49], v[44:45]
	v_pk_mul_f32 v[40:41], v[40:41], v[36:37]
	v_add_f32_e32 v123, 1.0, v123
	v_rcp_f32_e32 v124, v123
	v_mul_f32_e32 v123, 0xbfb8aa3b, v125
	v_exp_f32_e32 v123, v123
	v_pk_mul_f32 v[32:33], v[32:33], v[28:29]
	v_pk_mul_f32 v[24:25], v[24:25], v[20:21]
	v_pk_mul_f32 v[16:17], v[16:17], v[12:13]
	v_add_f32_e32 v123, 1.0, v123
	v_rcp_f32_e32 v125, v123
	v_pk_mul_f32 v[2:3], v[2:3], v[6:7]
	v_lshl_add_u32 v148, s26, 8, v144
	v_lshl_or_b32 v142, s24, 7, v146
	v_pk_mul_f32 v[124:125], v[128:129], v[124:125]
	v_ashrrev_i32_e32 v143, 31, v142
	v_cvt_pk_bf16_f32 v123, v124, v125
	v_pk_mul_f32 v[124:125], v[114:115], v[250:251] op_sel_hi:[1,0]
	v_exp_f32_e32 v124, v124
	v_exp_f32_e32 v125, v125
	v_pk_mul_f32 v[114:115], v[118:119], v[114:115]
	v_mov_b64_e32 v[140:141], s[6:7]
	v_pk_add_f32 v[124:125], v[124:125], 1.0 op_sel_hi:[1,0]
	v_rcp_f32_e32 v124, v124
	v_rcp_f32_e32 v125, v125
	v_pk_mul_f32 v[4:5], v[4:5], v[8:9]
	v_mad_i64_i32 v[150:151], s[24:25], v148, s86, v[140:141]
	v_pk_mul_f32 v[114:115], v[114:115], v[124:125]
	v_lshlrev_b64 v[142:143], 1, v[142:143]
	v_cvt_pk_bf16_f32 v124, v114, v115
	v_pk_mul_f32 v[114:115], v[116:117], v[250:251] op_sel_hi:[1,0]
	v_pk_mul_f32 v[116:117], v[106:107], v[250:251] op_sel_hi:[1,0]
	v_exp_f32_e32 v116, v116
	v_exp_f32_e32 v117, v117
	v_pk_mul_f32 v[106:107], v[110:111], v[106:107]
	v_exp_f32_e32 v114, v114
	v_pk_add_f32 v[116:117], v[116:117], 1.0 op_sel_hi:[1,0]
	v_rcp_f32_e32 v116, v116
	v_rcp_f32_e32 v117, v117
	v_exp_f32_e32 v115, v115
	s_nop 0
	v_pk_add_f32 v[114:115], v[114:115], 1.0 op_sel_hi:[1,0]
	v_rcp_f32_e32 v114, v114
	v_pk_mul_f32 v[106:107], v[106:107], v[116:117]
	v_cvt_pk_bf16_f32 v106, v106, v107
	v_mul_f32_e32 v107, 0xbfb8aa3b, v108
	v_exp_f32_e32 v107, v107
	v_rcp_f32_e32 v115, v115
	v_lshl_add_u64 v[150:151], v[150:151], 0, v[142:143]
	s_andn2_b64 vcc, exec, s[18:19]
	v_add_f32_e32 v107, 1.0, v107
	v_rcp_f32_e32 v108, v107
	v_mul_f32_e32 v107, 0xbfb8aa3b, v109
	v_exp_f32_e32 v107, v107
	v_pk_mul_f32 v[114:115], v[120:121], v[114:115]
	v_add_f32_e32 v107, 1.0, v107
	v_rcp_f32_e32 v109, v107
	v_cvt_pk_bf16_f32 v125, v114, v115
	v_or_b32_e32 v114, 16, v148
	v_mad_i64_i32 v[114:115], s[24:25], v114, s86, v[140:141]
	v_pk_mul_f32 v[108:109], v[112:113], v[108:109]
	v_lshl_add_u64 v[114:115], v[114:115], 0, v[142:143]
	v_cvt_pk_bf16_f32 v107, v108, v109
	v_pk_mul_f32 v[108:109], v[98:99], v[250:251] op_sel_hi:[1,0]
	v_exp_f32_e32 v108, v108
	v_exp_f32_e32 v109, v109
	v_pk_mul_f32 v[98:99], v[102:103], v[98:99]
	global_store_dwordx4 v[150:151], v[122:125], off
	v_pk_add_f32 v[108:109], v[108:109], 1.0 op_sel_hi:[1,0]
	v_rcp_f32_e32 v108, v108
	v_rcp_f32_e32 v109, v109
	s_nop 0
	v_pk_mul_f32 v[98:99], v[98:99], v[108:109]
	s_nop 0
	v_cvt_pk_bf16_f32 v108, v98, v99
	v_pk_mul_f32 v[98:99], v[100:101], v[250:251] op_sel_hi:[1,0]
	v_pk_mul_f32 v[100:101], v[90:91], v[250:251] op_sel_hi:[1,0]
	v_exp_f32_e32 v100, v100
	v_exp_f32_e32 v101, v101
	v_pk_mul_f32 v[90:91], v[94:95], v[90:91]
	v_exp_f32_e32 v98, v98
	v_pk_add_f32 v[100:101], v[100:101], 1.0 op_sel_hi:[1,0]
	v_rcp_f32_e32 v100, v100
	v_rcp_f32_e32 v101, v101
	v_exp_f32_e32 v99, v99
	s_nop 0
	v_pk_add_f32 v[98:99], v[98:99], 1.0 op_sel_hi:[1,0]
	v_rcp_f32_e32 v98, v98
	v_pk_mul_f32 v[90:91], v[90:91], v[100:101]
	v_cvt_pk_bf16_f32 v90, v90, v91
	v_mul_f32_e32 v91, 0xbfb8aa3b, v92
	v_exp_f32_e32 v91, v91
	v_rcp_f32_e32 v99, v99
	v_add_f32_e32 v91, 1.0, v91
	v_rcp_f32_e32 v92, v91
	v_mul_f32_e32 v91, 0xbfb8aa3b, v93
	v_exp_f32_e32 v91, v91
	v_pk_mul_f32 v[98:99], v[104:105], v[98:99]
	v_add_f32_e32 v91, 1.0, v91
	v_rcp_f32_e32 v93, v91
	v_cvt_pk_bf16_f32 v109, v98, v99
	v_or_b32_e32 v98, 32, v148
	v_mad_i64_i32 v[98:99], s[24:25], v98, s86, v[140:141]
	v_pk_mul_f32 v[92:93], v[96:97], v[92:93]
	v_lshl_add_u64 v[98:99], v[98:99], 0, v[142:143]
	v_cvt_pk_bf16_f32 v91, v92, v93
	v_pk_mul_f32 v[92:93], v[82:83], v[250:251] op_sel_hi:[1,0]
	v_exp_f32_e32 v92, v92
	v_exp_f32_e32 v93, v93
	v_pk_mul_f32 v[82:83], v[86:87], v[82:83]
	global_store_dwordx4 v[114:115], v[106:109], off
	v_pk_add_f32 v[92:93], v[92:93], 1.0 op_sel_hi:[1,0]
	v_rcp_f32_e32 v92, v92
	v_rcp_f32_e32 v93, v93
	s_nop 0
	v_pk_mul_f32 v[82:83], v[82:83], v[92:93]
	s_nop 0
	v_cvt_pk_bf16_f32 v92, v82, v83
	v_pk_mul_f32 v[82:83], v[84:85], v[250:251] op_sel_hi:[1,0]
	v_pk_mul_f32 v[84:85], v[74:75], v[250:251] op_sel_hi:[1,0]
	v_exp_f32_e32 v84, v84
	v_exp_f32_e32 v85, v85
	v_pk_mul_f32 v[74:75], v[78:79], v[74:75]
	v_exp_f32_e32 v82, v82
	v_pk_add_f32 v[84:85], v[84:85], 1.0 op_sel_hi:[1,0]
	v_rcp_f32_e32 v84, v84
	v_rcp_f32_e32 v85, v85
	v_exp_f32_e32 v83, v83
	s_nop 0
	v_pk_add_f32 v[82:83], v[82:83], 1.0 op_sel_hi:[1,0]
	v_rcp_f32_e32 v82, v82
	v_pk_mul_f32 v[74:75], v[74:75], v[84:85]
	v_cvt_pk_bf16_f32 v74, v74, v75
	v_mul_f32_e32 v75, 0xbfb8aa3b, v76
	v_exp_f32_e32 v75, v75
	v_rcp_f32_e32 v83, v83
	v_add_f32_e32 v75, 1.0, v75
	v_rcp_f32_e32 v76, v75
	v_mul_f32_e32 v75, 0xbfb8aa3b, v77
	v_exp_f32_e32 v75, v75
	v_pk_mul_f32 v[82:83], v[88:89], v[82:83]
	v_add_f32_e32 v75, 1.0, v75
	v_rcp_f32_e32 v77, v75
	v_cvt_pk_bf16_f32 v93, v82, v83
	v_or_b32_e32 v82, 48, v148
	v_mad_i64_i32 v[82:83], s[24:25], v82, s86, v[140:141]
	v_pk_mul_f32 v[76:77], v[80:81], v[76:77]
	v_lshl_add_u64 v[82:83], v[82:83], 0, v[142:143]
	v_cvt_pk_bf16_f32 v75, v76, v77
	v_pk_mul_f32 v[76:77], v[66:67], v[250:251] op_sel_hi:[1,0]
	v_exp_f32_e32 v76, v76
	v_exp_f32_e32 v77, v77
	v_pk_mul_f32 v[66:67], v[70:71], v[66:67]
	global_store_dwordx4 v[98:99], v[90:93], off
	v_pk_add_f32 v[76:77], v[76:77], 1.0 op_sel_hi:[1,0]
	v_rcp_f32_e32 v76, v76
	v_rcp_f32_e32 v77, v77
	s_nop 0
	v_pk_mul_f32 v[66:67], v[66:67], v[76:77]
	s_nop 0
	v_cvt_pk_bf16_f32 v76, v66, v67
	v_pk_mul_f32 v[66:67], v[68:69], v[250:251] op_sel_hi:[1,0]
	v_pk_mul_f32 v[68:69], v[58:59], v[250:251] op_sel_hi:[1,0]
	v_exp_f32_e32 v68, v68
	v_exp_f32_e32 v69, v69
	v_pk_mul_f32 v[58:59], v[62:63], v[58:59]
	v_exp_f32_e32 v66, v66
	v_pk_add_f32 v[68:69], v[68:69], 1.0 op_sel_hi:[1,0]
	v_rcp_f32_e32 v68, v68
	v_rcp_f32_e32 v69, v69
	v_exp_f32_e32 v67, v67
	s_nop 0
	v_pk_add_f32 v[66:67], v[66:67], 1.0 op_sel_hi:[1,0]
	v_rcp_f32_e32 v66, v66
	v_pk_mul_f32 v[58:59], v[58:59], v[68:69]
	v_cvt_pk_bf16_f32 v58, v58, v59
	v_mul_f32_e32 v59, 0xbfb8aa3b, v60
	v_exp_f32_e32 v59, v59
	v_rcp_f32_e32 v67, v67
	v_add_f32_e32 v59, 1.0, v59
	v_rcp_f32_e32 v60, v59
	v_mul_f32_e32 v59, 0xbfb8aa3b, v61
	v_exp_f32_e32 v59, v59
	v_pk_mul_f32 v[66:67], v[72:73], v[66:67]
	v_add_f32_e32 v59, 1.0, v59
	v_rcp_f32_e32 v61, v59
	v_cvt_pk_bf16_f32 v77, v66, v67
	v_add_u32_e32 v66, 0x80, v148
	v_mad_i64_i32 v[66:67], s[24:25], v66, s86, v[140:141]
	v_pk_mul_f32 v[60:61], v[64:65], v[60:61]
	v_lshl_add_u64 v[66:67], v[66:67], 0, v[142:143]
	v_cvt_pk_bf16_f32 v59, v60, v61
	v_pk_mul_f32 v[60:61], v[50:51], v[250:251] op_sel_hi:[1,0]
	v_exp_f32_e32 v60, v60
	v_exp_f32_e32 v61, v61
	v_pk_mul_f32 v[50:51], v[54:55], v[50:51]
	global_store_dwordx4 v[82:83], v[74:77], off
	v_pk_add_f32 v[60:61], v[60:61], 1.0 op_sel_hi:[1,0]
	v_rcp_f32_e32 v60, v60
	v_rcp_f32_e32 v61, v61
	s_nop 0
	v_pk_mul_f32 v[50:51], v[50:51], v[60:61]
	s_nop 0
	v_cvt_pk_bf16_f32 v60, v50, v51
	v_pk_mul_f32 v[50:51], v[52:53], v[250:251] op_sel_hi:[1,0]
	v_pk_mul_f32 v[52:53], v[42:43], v[250:251] op_sel_hi:[1,0]
	v_exp_f32_e32 v52, v52
	v_exp_f32_e32 v53, v53
	v_pk_mul_f32 v[42:43], v[46:47], v[42:43]
	v_exp_f32_e32 v50, v50
	v_pk_add_f32 v[52:53], v[52:53], 1.0 op_sel_hi:[1,0]
	v_rcp_f32_e32 v52, v52
	v_rcp_f32_e32 v53, v53
	v_exp_f32_e32 v51, v51
	s_nop 0
	v_pk_add_f32 v[50:51], v[50:51], 1.0 op_sel_hi:[1,0]
	v_rcp_f32_e32 v50, v50
	v_pk_mul_f32 v[42:43], v[42:43], v[52:53]
	v_cvt_pk_bf16_f32 v42, v42, v43
	v_mul_f32_e32 v43, 0xbfb8aa3b, v44
	v_exp_f32_e32 v43, v43
	v_rcp_f32_e32 v51, v51
	v_add_f32_e32 v43, 1.0, v43
	v_rcp_f32_e32 v44, v43
	v_mul_f32_e32 v43, 0xbfb8aa3b, v45
	v_exp_f32_e32 v43, v43
	v_pk_mul_f32 v[50:51], v[56:57], v[50:51]
	v_add_f32_e32 v43, 1.0, v43
	v_rcp_f32_e32 v45, v43
	v_cvt_pk_bf16_f32 v61, v50, v51
	v_add_u32_e32 v50, 0x90, v148
	v_mad_i64_i32 v[50:51], s[24:25], v50, s86, v[140:141]
	v_pk_mul_f32 v[44:45], v[48:49], v[44:45]
	v_lshl_add_u64 v[50:51], v[50:51], 0, v[142:143]
	v_cvt_pk_bf16_f32 v43, v44, v45
	v_pk_mul_f32 v[44:45], v[34:35], v[250:251] op_sel_hi:[1,0]
	v_exp_f32_e32 v44, v44
	v_exp_f32_e32 v45, v45
	v_pk_mul_f32 v[34:35], v[38:39], v[34:35]
	global_store_dwordx4 v[66:67], v[58:61], off
	v_pk_add_f32 v[44:45], v[44:45], 1.0 op_sel_hi:[1,0]
	v_rcp_f32_e32 v44, v44
	v_rcp_f32_e32 v45, v45
	s_nop 0
	v_pk_mul_f32 v[34:35], v[34:35], v[44:45]
	s_nop 0
	v_cvt_pk_bf16_f32 v44, v34, v35
	v_pk_mul_f32 v[34:35], v[36:37], v[250:251] op_sel_hi:[1,0]
	v_pk_mul_f32 v[36:37], v[26:27], v[250:251] op_sel_hi:[1,0]
	v_exp_f32_e32 v36, v36
	v_exp_f32_e32 v37, v37
	v_pk_mul_f32 v[26:27], v[30:31], v[26:27]
	v_exp_f32_e32 v34, v34
	v_pk_add_f32 v[36:37], v[36:37], 1.0 op_sel_hi:[1,0]
	v_rcp_f32_e32 v36, v36
	v_rcp_f32_e32 v37, v37
	v_exp_f32_e32 v35, v35
	s_nop 0
	v_pk_add_f32 v[34:35], v[34:35], 1.0 op_sel_hi:[1,0]
	v_rcp_f32_e32 v34, v34
	v_pk_mul_f32 v[26:27], v[26:27], v[36:37]
	v_cvt_pk_bf16_f32 v26, v26, v27
	v_mul_f32_e32 v27, 0xbfb8aa3b, v28
	v_exp_f32_e32 v27, v27
	v_rcp_f32_e32 v35, v35
	v_add_f32_e32 v27, 1.0, v27
	v_rcp_f32_e32 v28, v27
	v_mul_f32_e32 v27, 0xbfb8aa3b, v29
	v_exp_f32_e32 v27, v27
	v_pk_mul_f32 v[34:35], v[40:41], v[34:35]
	v_add_f32_e32 v27, 1.0, v27
	v_rcp_f32_e32 v29, v27
	v_cvt_pk_bf16_f32 v45, v34, v35
	v_add_u32_e32 v34, 0xa0, v148
	v_mad_i64_i32 v[34:35], s[24:25], v34, s86, v[140:141]
	v_pk_mul_f32 v[28:29], v[32:33], v[28:29]
	v_lshl_add_u64 v[34:35], v[34:35], 0, v[142:143]
	v_cvt_pk_bf16_f32 v27, v28, v29
	v_pk_mul_f32 v[28:29], v[18:19], v[250:251] op_sel_hi:[1,0]
	v_exp_f32_e32 v28, v28
	v_exp_f32_e32 v29, v29
	v_pk_mul_f32 v[18:19], v[22:23], v[18:19]
	global_store_dwordx4 v[50:51], v[42:45], off
	v_pk_add_f32 v[28:29], v[28:29], 1.0 op_sel_hi:[1,0]
	v_rcp_f32_e32 v28, v28
	v_rcp_f32_e32 v29, v29
	s_nop 0
	v_pk_mul_f32 v[18:19], v[18:19], v[28:29]
	s_nop 0
	v_cvt_pk_bf16_f32 v28, v18, v19
	v_pk_mul_f32 v[18:19], v[20:21], v[250:251] op_sel_hi:[1,0]
	v_pk_mul_f32 v[20:21], v[10:11], v[250:251] op_sel_hi:[1,0]
	v_exp_f32_e32 v20, v20
	v_exp_f32_e32 v21, v21
	v_pk_mul_f32 v[10:11], v[14:15], v[10:11]
	v_exp_f32_e32 v18, v18
	v_pk_add_f32 v[20:21], v[20:21], 1.0 op_sel_hi:[1,0]
	v_rcp_f32_e32 v20, v20
	v_rcp_f32_e32 v21, v21
	v_exp_f32_e32 v19, v19
	s_nop 0
	v_pk_add_f32 v[18:19], v[18:19], 1.0 op_sel_hi:[1,0]
	v_rcp_f32_e32 v18, v18
	v_pk_mul_f32 v[10:11], v[10:11], v[20:21]
	v_cvt_pk_bf16_f32 v10, v10, v11
	v_mul_f32_e32 v11, 0xbfb8aa3b, v12
	v_exp_f32_e32 v11, v11
	v_rcp_f32_e32 v19, v19
	v_add_f32_e32 v11, 1.0, v11
	v_rcp_f32_e32 v12, v11
	v_mul_f32_e32 v11, 0xbfb8aa3b, v13
	v_exp_f32_e32 v11, v11
	v_pk_mul_f32 v[18:19], v[24:25], v[18:19]
	v_add_f32_e32 v11, 1.0, v11
	v_rcp_f32_e32 v13, v11
	v_cvt_pk_bf16_f32 v29, v18, v19
	v_add_u32_e32 v18, 0xb0, v148
	v_mad_i64_i32 v[18:19], s[24:25], v18, s86, v[140:141]
	v_pk_mul_f32 v[12:13], v[16:17], v[12:13]
	v_lshl_add_u64 v[18:19], v[18:19], 0, v[142:143]
	v_cvt_pk_bf16_f32 v11, v12, v13
	v_pk_mul_f32 v[12:13], v[6:7], v[250:251] op_sel_hi:[1,0]
	v_exp_f32_e32 v12, v12
	v_exp_f32_e32 v13, v13
	s_mov_b64 s[24:25], -1
	global_store_dwordx4 v[34:35], v[26:29], off
	v_pk_add_f32 v[12:13], v[12:13], 1.0 op_sel_hi:[1,0]
	v_rcp_f32_e32 v12, v12
	v_rcp_f32_e32 v13, v13
	s_nop 0
	v_pk_mul_f32 v[2:3], v[2:3], v[12:13]
	s_nop 0
	v_cvt_pk_bf16_f32 v12, v2, v3
	v_pk_mul_f32 v[2:3], v[8:9], v[250:251] op_sel_hi:[1,0]
	v_exp_f32_e32 v2, v2
	v_exp_f32_e32 v3, v3
	s_nop 0
	v_pk_add_f32 v[2:3], v[2:3], 1.0 op_sel_hi:[1,0]
	v_rcp_f32_e32 v2, v2
	v_rcp_f32_e32 v3, v3
	s_nop 0
	v_pk_mul_f32 v[2:3], v[4:5], v[2:3]
	s_nop 0
	v_cvt_pk_bf16_f32 v13, v2, v3
	global_store_dwordx4 v[18:19], v[10:13], off
	s_cbranch_vccnz .LBB0_367
	s_andn2_b64 vcc, exec, s[4:5]
	s_cbranch_vccnz .LBB0_366
	s_barrier
	s_branch .LBB0_366

	.amdhsa_kernel _Z14fwd_megakernel4Args
		.amdhsa_group_segment_fixed_size 0
		.amdhsa_private_segment_fixed_size 0
		.amdhsa_kernarg_size 424
		.amdhsa_user_sgpr_count 2
		.amdhsa_user_sgpr_dispatch_ptr 0
		.amdhsa_user_sgpr_queue_ptr 0
		.amdhsa_user_sgpr_kernarg_segment_ptr 1
		.amdhsa_user_sgpr_dispatch_id 0
		.amdhsa_user_sgpr_kernarg_preload_length 0
		.amdhsa_user_sgpr_kernarg_preload_offset 0
		.amdhsa_user_sgpr_private_segment_size 0
		.amdhsa_uses_dynamic_stack 0
		.amdhsa_enable_private_segment 0
		.amdhsa_system_sgpr_workgroup_id_x 1
		.amdhsa_system_sgpr_workgroup_id_y 0
		.amdhsa_system_sgpr_workgroup_id_z 0
		.amdhsa_system_sgpr_workgroup_info 0
		.amdhsa_system_vgpr_workitem_id 2
		.amdhsa_next_free_vgpr 252
		.amdhsa_next_free_sgpr 100
		.amdhsa_accum_offset 252
		.amdhsa_reserve_vcc 1
		.amdhsa_float_round_mode_32 0
		.amdhsa_float_round_mode_16_64 0
		.amdhsa_float_denorm_mode_32 3
		.amdhsa_float_denorm_mode_16_64 3
		.amdhsa_dx10_clamp 1
		.amdhsa_ieee_mode 1
		.amdhsa_fp16_overflow 0
		.amdhsa_tg_split 0
		.amdhsa_exception_fp_ieee_invalid_op 0
		.amdhsa_exception_fp_denorm_src 0
		.amdhsa_exception_fp_ieee_div_zero 0
		.amdhsa_exception_fp_ieee_overflow 0
		.amdhsa_exception_fp_ieee_underflow 0
		.amdhsa_exception_fp_ieee_inexact 0
		.amdhsa_exception_int_div_zero 0
	.end_amdhsa_kernel

.Lfunc_end0:
	.size	_Z14fwd_megakernel4Args, .Lfunc_end0-_Z14fwd_megakernel4Args
	.set _Z14fwd_megakernel4Args.num_vgpr, 252
	.set _Z14fwd_megakernel4Args.num_agpr, 0
	.set _Z14fwd_megakernel4Args.numbered_sgpr, 100
	.set _Z14fwd_megakernel4Args.num_named_barrier, 0
	.set _Z14fwd_megakernel4Args.private_seg_size, 0
	.set _Z14fwd_megakernel4Args.uses_vcc, 1
	.set _Z14fwd_megakernel4Args.uses_flat_scratch, 0
	.set _Z14fwd_megakernel4Args.has_dyn_sized_stack, 0
	.set _Z14fwd_megakernel4Args.has_recursion, 0
	.set _Z14fwd_megakernel4Args.has_indirect_call, 0

amdhsa.kernels:
  - .agpr_count:     0
    .args:
      - .offset:         0
        .size:           168
        .value_kind:     by_value
      - .offset:         168
        .size:           4
        .value_kind:     hidden_block_count_x
      - .offset:         172
        .size:           4
        .value_kind:     hidden_block_count_y
      - .offset:         176
        .size:           4
        .value_kind:     hidden_block_count_z
      - .offset:         180
        .size:           2
        .value_kind:     hidden_group_size_x
      - .offset:         182
        .size:           2
        .value_kind:     hidden_group_size_y
      - .offset:         184
        .size:           2
        .value_kind:     hidden_group_size_z
      - .offset:         186
        .size:           2
        .value_kind:     hidden_remainder_x
      - .offset:         188
        .size:           2
        .value_kind:     hidden_remainder_y
      - .offset:         190
        .size:           2
        .value_kind:     hidden_remainder_z
      - .offset:         208
        .size:           8
        .value_kind:     hidden_global_offset_x
      - .offset:         216
        .size:           8
        .value_kind:     hidden_global_offset_y
      - .offset:         224
        .size:           8
        .value_kind:     hidden_global_offset_z
      - .offset:         232
        .size:           2
        .value_kind:     hidden_grid_dims
      - .offset:         256
        .size:           8
        .value_kind:     hidden_multigrid_sync_arg
      - .offset:         288
        .size:           4
        .value_kind:     hidden_dynamic_lds_size
    .group_segment_fixed_size: 0
    .kernarg_segment_align: 8
    .kernarg_segment_size: 424
    .language:       OpenCL C
    .language_version:
      - 2
      - 0
    .max_flat_workgroup_size: 512
    .name:           _Z14fwd_megakernel4Args
    .private_segment_fixed_size: 0
    .sgpr_count:     106
    .sgpr_spill_count: 76
    .symbol:         _Z14fwd_megakernel4Args.kd
    .uniform_work_group_size: 1
    .uses_dynamic_stack: false
    .vgpr_count:     252
    .vgpr_spill_count: 0
    .wavefront_size: 64
